# acquire invalidate issued before the counter spin loop in the GEMM-side wait (the CU is idle, nothing can repopulate its L1), so it overlaps the polling
# speedup vs baseline: 1.0010x; 1.0010x over previous
.Lhf_poll:
	s_lshl_b32 s8, s8, 4
	s_lshl_b32 s9, s9, 4
	s_lshl_b32 s10, s10, 4
	s_add_i32 s8, s8, 0x3e00
	s_add_i32 s9, s9, 0x3e00
	s_add_i32 s10, s10, 0x3e00
	v_mov_b32_e32 v3, s8
	v_mov_b32_e32 v4, s9
	v_mov_b32_e32 v5, s10
	v_mbcnt_lo_u32_b32 v10, -1, 0
	v_mbcnt_hi_u32_b32 v10, -1, v10
	v_and_b32_e32 v10, 31, v10
	v_lshlrev_b32_e32 v10, 5, v10
	v_add_u32_e32 v10, 0x3a00, v10
	s_waitcnt lgkmcnt(0)
	s_add_u32 s6, s6, 0xe800000
	s_addc_u32 s7, s7, 0
	buffer_inv sc1

.Lhf_slp:
	s_sleep 2
	s_branch .Lhf_loop
.Lhf_rel:
	s_waitcnt vmcnt(0)
.Lhf_done:
	s_barrier
	s_cmp_eq_u32 s51, 1
	s_cbranch_scc1 .LBB0_408
	s_mov_b64 s[8:9], s[66:67]
	v_mov_b32_e32 v0, v1
	s_load_dwordx2 s[10:11], s[8:9], 0x100
	v_mbcnt_lo_u32_b32 v0, -1, v0
	v_mbcnt_hi_u32_b32 v144, -1, v0
	v_readlane_b32 s0, v254, 8
	v_add_u32_e32 v0, s86, v144
	v_readlane_b32 s1, v254, 9
	s_lshr_b32 s52, s51, 1
	v_readfirstlane_b32 s4, v0
	s_andn2_b64 vcc, exec, s[0:1]
	v_readlane_b32 s0, v255, 16
	s_ashr_i32 s30, s4, 6
	s_add_i32 s52, s52, s0
	s_cbranch_vccnz .LBB0_410
	v_lshlrev_b32_e32 v2, 4, v0
	v_add_u32_e32 v3, 0x2000, v2
	v_ashrrev_i32_e32 v4, 31, v3
	v_lshrrev_b32_e32 v4, 22, v4
	v_add_u32_e32 v4, v3, v4
	v_ashrrev_i32_e32 v10, 10, v4
	v_mul_i32_i24_e32 v4, 0x400, v10
	v_sub_u32_e32 v3, v3, v4
	v_lshrrev_b32_e32 v4, 4, v3
	v_bitop3_b32 v3, v4, v3, 32 bitop3:0x6c
	v_ashrrev_i32_e32 v4, 31, v3
	v_lshrrev_b32_e32 v4, 26, v4
	v_add_u32_e32 v4, v3, v4
	v_lshlrev_b32_e32 v5, 3, v10
	v_ashrrev_i32_e32 v11, 6, v4
	v_and_b32_e32 v5, -16, v5
	v_add_u32_e32 v5, v11, v5
	v_and_b32_e32 v6, 3, v11
	s_mov_b32 s6, 0x1fffe0
	v_lshrrev_b32_e32 v7, 2, v5
	v_lshlrev_b32_e32 v8, 1, v5
	v_and_b32_e32 v4, 0xc0, v4
	v_and_or_b32 v6, v5, s6, v6
	v_and_b32_e32 v7, 4, v7
	v_and_b32_e32 v8, 24, v8
	v_sub_u32_e32 v3, v3, v4
	v_or3_b32 v6, v6, v7, v8
	v_lshlrev_b32_e32 v7, 5, v10
	v_ashrrev_i16_sdwa v3, v236, sext(v3) dst_sel:DWORD dst_unused:UNUSED_PAD src0_sel:DWORD src1_sel:BYTE_0
	v_and_b32_e32 v7, 32, v7
	v_bfe_i32 v12, v3, 0, 16
	v_add_lshl_u32 v3, v7, v12, 1
	v_lshl_add_u32 v130, v6, 11, v3
	v_lshl_add_u32 v132, v5, 11, v3
	v_bfe_i32 v3, v0, 27, 1
	v_lshrrev_b32_e32 v3, 22, v3
	v_add_u32_e32 v3, v2, v3
	v_and_b32_e32 v3, 0xfffffc00, v3
	v_sub_u32_e32 v2, v2, v3
	v_lshrrev_b32_e32 v3, 4, v2
	v_ashrrev_i32_e32 v4, 31, v0
	v_bitop3_b32 v2, v3, v2, 32 bitop3:0x6c
	v_lshrrev_b32_e32 v4, 26, v4
	v_ashrrev_i32_e32 v3, 31, v2
	v_add_u32_e32 v0, v0, v4
	v_lshrrev_b32_e32 v3, 26, v3
	v_ashrrev_i32_e32 v14, 6, v0
	v_add_u32_e32 v3, v2, v3
	v_lshlrev_b32_e32 v0, 3, v14
	v_ashrrev_i32_e32 v13, 6, v3
	v_and_b32_e32 v0, -16, v0
	s_waitcnt lgkmcnt(0)
	s_add_u32 s0, s10, 0x5c00000
	v_add_u32_e32 v4, v13, v0
	s_addc_u32 s1, s11, 0
	s_mul_i32 s2, s52, 0xb00000
	v_and_b32_e32 v0, 3, v13
	v_lshrrev_b32_e32 v5, 2, v4
	v_lshlrev_b32_e32 v6, 1, v4
	v_and_b32_e32 v3, 0xc0, v3
	s_mul_hi_u32 s3, s52, 0xb00000
	s_add_u32 s2, s10, s2
	v_and_or_b32 v0, v4, s6, v0
	v_and_b32_e32 v5, 4, v5
	v_and_b32_e32 v6, 24, v6
	v_sub_u32_e32 v2, v2, v3
	s_addc_u32 s3, s11, s3
	s_ashr_i32 s5, s4, 8
	s_lshl_b32 s31, s30, 10
	v_or3_b32 v0, v0, v5, v6
	v_lshlrev_b32_e32 v5, 5, v14
	v_ashrrev_i16_sdwa v2, v236, sext(v2) dst_sel:DWORD dst_unused:UNUSED_PAD src0_sel:DWORD src1_sel:BYTE_0
	v_readlane_b32 s6, v254, 15
	v_and_b32_e32 v5, 32, v5
	v_bfe_i32 v15, v2, 0, 16
	v_readlane_b32 s7, v254, 16
	s_add_u32 s24, s2, s6
	v_add_lshl_u32 v2, v5, v15, 1
	s_addc_u32 s25, s3, s7
	s_add_i32 s33, s31, 0
	v_lshl_add_u32 v0, v0, 11, v2
	s_add_i32 m0, s33, 0x10000
	v_readlane_b32 s6, v254, 13
	global_load_lds_dwordx4 v0, s[24:25]
	s_add_i32 m0, s33, 0x12000
	v_readlane_b32 s7, v254, 14
	s_add_u32 s26, s0, s6
	s_addc_u32 s27, s1, s7
	s_add_u32 s6, s24, 0x40000
	global_load_lds_dwordx4 v130, s[24:25]
	s_addc_u32 s7, s25, 0
	s_add_i32 m0, s33, 0x14000
	s_add_i32 s34, s33, 0x2000
	global_load_lds_dwordx4 v0, s[6:7]
	s_add_i32 m0, s33, 0x16000
	v_lshl_add_u32 v134, v4, 11, v2
	global_load_lds_dwordx4 v130, s[6:7]
	s_mov_b32 m0, s33
	s_add_u32 s6, s26, 0x40000
	global_load_lds_dwordx4 v134, s[26:27]
	s_mov_b32 m0, s34
	s_addc_u32 s7, s27, 0
	s_add_i32 s35, s33, 0x4000
	global_load_lds_dwordx4 v132, s[26:27]
	s_mov_b32 m0, s35
	s_add_i32 s36, s33, 0x6000
	global_load_lds_dwordx4 v134, s[6:7]
	s_mov_b32 m0, s36
	v_mov_b32_e32 v131, v1
	global_load_lds_dwordx4 v132, s[6:7]
	v_mov_b32_e32 v135, v1
	v_mov_b32_e32 v133, v1
	s_cmp_eq_u32 s5, 1
	v_lshl_add_u64 v[8:9], s[24:25], 0, v[0:1]
	v_lshl_add_u64 v[6:7], s[24:25], 0, v[130:131]
	v_lshl_add_u64 v[2:3], s[26:27], 0, v[134:135]
	s_cselect_b64 s[14:15], -1, 0
	s_cmp_lg_u32 s5, 1
	v_lshl_add_u64 v[4:5], s[26:27], 0, v[132:133]
	s_cbranch_scc1 .LBB0_392
	s_barrier
